# flash units: static priority raise moved to waves 0-3 (per-half comparison of the baseline's one raise)
# speedup vs baseline: 1.0036x; 1.0036x over previous
; template <int DQK, int NSUB, int MODE>
; __device__ __forceinline__ void flash_unit(LAS char* L, const bf16_t* Qp, int qpitch, const bf16_t* Kp, int kpitch, const bf16_t* Vp, int vpitch,
;                                            bf16_t* Op, int opitch, float lam, float oscale, const float* subln) {
;     ...
;     const int kr1 = tid / KCH, kc1 = tid % KCH, kr2 = (tid + 512) / KCH, kc2 = (tid + 512) % KCH; const bool has2 = (tid + 512) < NKCH;
;     const int vr1 = tid >> 3, vc1 = tid & 7;
;     const bf16_t* kg1 = Kp + (size_t)kr1 * kpitch + kc1 * 8; const bf16_t* kg2 = Kp + (size_t)kr2 * kpitch + kc2 * 8; const bf16_t* vg1 = Vp + (size_t)vr1 * vpitch + vc1 * 8;
;     const int kl1 = kr1 * KPB + kc1 * 16, kl2 = kr2 * KPB + kc2 * 16, vl1 = vr1 * VPB + vc1 * 16;
;     u32x4 rk1, rk2 = {0u, 0u, 0u, 0u}, rv1;
;     float mref[NSUB], lrow[NSUB]; f32x16 o[NSUB][2], negm[NSUB];
; #pragma unroll
;     for (int s = 0; s < NSUB; ++s) { mref[s] = 0.f; lrow[s] = 0.f;
; #pragma unroll
;         for (int r = 0; r < 16; ++r) { o[s][0][r] = 0.f; o[s][1][r] = 0.f; negm[s][r] = 0.f; } }
;     rk1 = *(const u32x4*)kg1; if (has2) rk2 = *(const u32x4*)kg2; rv1 = *(const u32x4*)vg1;
;     __syncthreads();
;     *(u32x4*)(Lg + kl1) = rk1; if (has2) *(u32x4*)(Lg + kl2) = rk2; *(u32x4*)(Lg + OFF_V + vl1) = rv1;
;     __syncthreads();
;     const int vq = (lane & 15) >> 2, vp_ = lane & 3, vblk = (lane >> 4) & 1;
;     const int voff = (4 * hi + vq) * VPB + (16 * vblk + 4 * vp_) * 2;
;     if (__builtin_amdgcn_readfirstlane(wid) >= 4) __builtin_amdgcn_s_setprio(1);
.LBB0_558:
	s_or_b64 exec, exec, s[8:9]
	v_ashrrev_i32_e32 v106, 3, v15
	v_and_b32_e32 v12, 7, v15
	v_mov_b64_e32 v[6:7], s[10:11]
	v_mad_i64_i32 v[6:7], s[8:9], v106, s56, v[6:7]
	v_lshlrev_b32_e32 v86, 4, v12
	v_mov_b32_e32 v87, v193
	v_lshl_add_u64 v[12:13], v[6:7], 0, v[86:87]
	v_mul_lo_u32 v6, v81, s27
	v_lshl_add_u32 v188, v5, 4, v6
	v_mul_lo_u32 v5, v33, s27
	v_lshl_add_u32 v189, v4, 4, v5
	global_load_dwordx4 v[4:7], v[12:13], off offset:1024
	v_add_u32_e32 v107, 0, v189
	v_add_u32_e32 v87, 0, v188
	s_waitcnt lgkmcnt(0)
	s_barrier
	s_waitcnt vmcnt(0)
	ds_write_b128 v107, v[0:3]
	s_and_saveexec_b64 s[8:9], s[36:37]
	ds_write_b128 v87, v[144:147]
	s_or_b64 exec, exec, s[8:9]
	v_mul_lo_u32 v0, v106, s27
	v_readfirstlane_b32 s8, v17
	v_add3_u32 v190, 0, v0, v86
	s_cmp_ge_i32 s8, 4
	ds_write_b128 v190, v[4:7] offset:18432
	s_waitcnt lgkmcnt(0)
	s_barrier
	s_cbranch_scc1 .LBB0_562
	s_setprio 1

; template <int DQK, int NSUB, int MODE>
; __device__ __forceinline__ void flash_unit(LAS char* L, const bf16_t* Qp, int qpitch, const bf16_t* Kp, int kpitch, const bf16_t* Vp, int vpitch,
;                                            bf16_t* Op, int opitch, float lam, float oscale, const float* subln) {
;     ...
;     const int kr1 = tid / KCH, kc1 = tid % KCH, kr2 = (tid + 512) / KCH, kc2 = (tid + 512) % KCH; const bool has2 = (tid + 512) < NKCH;
;     const int vr1 = tid >> 3, vc1 = tid & 7;
;     const bf16_t* kg1 = Kp + (size_t)kr1 * kpitch + kc1 * 8; const bf16_t* kg2 = Kp + (size_t)kr2 * kpitch + kc2 * 8; const bf16_t* vg1 = Vp + (size_t)vr1 * vpitch + vc1 * 8;
;     const int kl1 = kr1 * KPB + kc1 * 16, kl2 = kr2 * KPB + kc2 * 16, vl1 = vr1 * VPB + vc1 * 16;
;     u32x4 rk1, rk2 = {0u, 0u, 0u, 0u}, rv1;
;     float mref[NSUB], lrow[NSUB]; f32x16 o[NSUB][2], negm[NSUB];
; #pragma unroll
;     for (int s = 0; s < NSUB; ++s) { mref[s] = 0.f; lrow[s] = 0.f;
; #pragma unroll
;         for (int r = 0; r < 16; ++r) { o[s][0][r] = 0.f; o[s][1][r] = 0.f; negm[s][r] = 0.f; } }
;     rk1 = *(const u32x4*)kg1; if (has2) rk2 = *(const u32x4*)kg2; rv1 = *(const u32x4*)vg1;
;     __syncthreads();
;     *(u32x4*)(Lg + kl1) = rk1; if (has2) *(u32x4*)(Lg + kl2) = rk2; *(u32x4*)(Lg + OFF_V + vl1) = rv1;
;     __syncthreads();
;     const int vq = (lane & 15) >> 2, vp_ = lane & 3, vblk = (lane >> 4) & 1;
;     const int voff = (4 * hi + vq) * VPB + (16 * vblk + 4 * vp_) * 2;
;     if (__builtin_amdgcn_readfirstlane(wid) >= 4) __builtin_amdgcn_s_setprio(1);
.LBB0_594:
	s_or_b64 exec, exec, s[8:9]
	s_lshl_b64 s[14:15], s[14:15], 20
	s_add_u32 s8, s6, s14
	s_addc_u32 s9, s7, s15
	s_lshl_b32 s21, s20, 7
	v_ashrrev_i32_e32 v14, 3, v17
	s_add_u32 s8, s8, s21
	v_ashrrev_i32_e32 v15, 31, v14
	s_addc_u32 s9, s9, 0
	v_and_b32_e32 v6, 7, v17
	v_lshlrev_b64 v[40:41], 9, v[14:15]
	v_lshl_add_u64 v[4:5], s[8:9], 0, v[40:41]
	v_lshlrev_b32_e32 v38, 4, v6
	v_mov_b32_e32 v39, v193
	v_lshl_add_u64 v[12:13], v[4:5], 0, v[38:39]
	v_add_co_u32_e32 v4, vcc, 0x254c8000, v12
	v_mul_lo_u32 v15, v58, s18
	s_nop 0
	v_addc_co_u32_e32 v5, vcc, 0, v13, vcc
	global_load_dwordx4 v[4:7], v[4:5], off
	v_lshl_add_u32 v126, v21, 4, v15
	v_mul_lo_u32 v15, v33, s18
	v_lshl_add_u32 v127, v20, 4, v15
	v_add_u32_e32 v59, 0, v127
	v_add_u32_e32 v39, 0, v126
	s_waitcnt lgkmcnt(0)
	s_barrier
	s_waitcnt vmcnt(0)
	ds_write_b128 v59, v[0:3]
	s_and_saveexec_b64 s[8:9], s[36:37]
	ds_write_b128 v39, v[104:107]
	s_or_b64 exec, exec, s[8:9]
	v_mul_lo_u32 v0, v14, s27
	v_readfirstlane_b32 s8, v19
	v_add3_u32 v128, 0, v0, v38
	s_cmp_ge_i32 s8, 4
	ds_write_b128 v128, v[4:7] offset:26624
	s_waitcnt lgkmcnt(0)
	s_barrier
	s_cbranch_scc1 .LBB0_598
	s_setprio 1

; template <int DQK, int NSUB, int MODE>
; __device__ __forceinline__ void flash_unit(LAS char* L, const bf16_t* Qp, int qpitch, const bf16_t* Kp, int kpitch, const bf16_t* Vp, int vpitch,
;                                            bf16_t* Op, int opitch, float lam, float oscale, const float* subln) {
;     ...
;     const int kr1 = tid / KCH, kc1 = tid % KCH, kr2 = (tid + 512) / KCH, kc2 = (tid + 512) % KCH; const bool has2 = (tid + 512) < NKCH;
;     const int vr1 = tid >> 3, vc1 = tid & 7;
;     const bf16_t* kg1 = Kp + (size_t)kr1 * kpitch + kc1 * 8; const bf16_t* kg2 = Kp + (size_t)kr2 * kpitch + kc2 * 8; const bf16_t* vg1 = Vp + (size_t)vr1 * vpitch + vc1 * 8;
;     const int kl1 = kr1 * KPB + kc1 * 16, kl2 = kr2 * KPB + kc2 * 16, vl1 = vr1 * VPB + vc1 * 16;
;     u32x4 rk1, rk2 = {0u, 0u, 0u, 0u}, rv1;
;     float mref[NSUB], lrow[NSUB]; f32x16 o[NSUB][2], negm[NSUB];
; #pragma unroll
;     for (int s = 0; s < NSUB; ++s) { mref[s] = 0.f; lrow[s] = 0.f;
; #pragma unroll
;         for (int r = 0; r < 16; ++r) { o[s][0][r] = 0.f; o[s][1][r] = 0.f; negm[s][r] = 0.f; } }
;     rk1 = *(const u32x4*)kg1; if (has2) rk2 = *(const u32x4*)kg2; rv1 = *(const u32x4*)vg1;
;     __syncthreads();
;     *(u32x4*)(Lg + kl1) = rk1; if (has2) *(u32x4*)(Lg + kl2) = rk2; *(u32x4*)(Lg + OFF_V + vl1) = rv1;
;     __syncthreads();
;     const int vq = (lane & 15) >> 2, vp_ = lane & 3, vblk = (lane >> 4) & 1;
;     const int voff = (4 * hi + vq) * VPB + (16 * vblk + 4 * vp_) * 2;
;     if (__builtin_amdgcn_readfirstlane(wid) >= 4) __builtin_amdgcn_s_setprio(1);
.LBB0_623:
	s_or_b64 exec, exec, s[8:9]
	v_ashrrev_i32_e32 v65, 3, v15
	v_and_b32_e32 v12, 7, v15
	v_mov_b64_e32 v[6:7], s[10:11]
	v_mad_i64_i32 v[6:7], s[8:9], v65, s56, v[6:7]
	v_lshlrev_b32_e32 v44, 4, v12
	v_mov_b32_e32 v45, v193
	v_lshl_add_u64 v[12:13], v[6:7], 0, v[44:45]
	v_mul_lo_u32 v6, v64, s27
	v_lshl_add_u32 v136, v5, 4, v6
	v_mul_lo_u32 v5, v49, s27
	v_lshl_add_u32 v137, v4, 4, v5
	global_load_dwordx4 v[4:7], v[12:13], off offset:3840
	v_add_u32_e32 v66, 0, v137
	v_add_u32_e32 v45, 0, v136
	s_waitcnt lgkmcnt(0)
	s_barrier
	s_waitcnt vmcnt(0)
	ds_write_b128 v66, v[0:3]
	s_and_saveexec_b64 s[8:9], s[36:37]
	ds_write_b128 v45, v[112:115]
	s_or_b64 exec, exec, s[8:9]
	v_mul_lo_u32 v0, v65, s27
	v_readfirstlane_b32 s8, v17
	v_add3_u32 v138, 0, v0, v44
	s_cmp_ge_i32 s8, 4
	ds_write_b128 v138, v[4:7] offset:18432
	s_waitcnt lgkmcnt(0)
	s_barrier
	s_cbranch_scc1 .LBB0_627
	s_setprio 1
